# conv_gu loop handles two items per trip with both items' loads in flight (scale loads hoisted)
# speedup vs baseline: 1.0072x; 1.0072x over previous
.LBB0_65:
	s_mul_hi_i32 s46, s45, 0x2fa0be83
	s_lshr_b32 s47, s46, 31
	s_ashr_i32 s46, s46, 6
	s_add_i32 s84, s46, s47
	s_mul_i32 s46, s84, 0xffffd500
	s_mul_i32 s47, s84, 0xffffaa00
	s_add_i32 s46, s43, s46
	s_add_i32 s47, s44, s47
	s_and_b32 s48, s46, 0x60
	s_and_b32 s47, s47, 0xffffff00
	s_or_b32 s48, s48, s40
	s_mul_i32 s80, s84, 0x2b0000
	s_or_b32 s48, s48, s47
	s_mul_hi_i32 s49, s84, 0x2b0000
	s_add_u32 s80, s42, s80
	s_addc_u32 s49, s41, s49
	s_ashr_i32 s47, s46, 31
	s_lshl_b64 s[46:47], s[46:47], 2
	s_add_u32 s46, s80, s46
	s_addc_u32 s47, s49, s47
	v_mov_b32_e32 v13, v143
	v_mov_b32_e32 v15, v143
	v_mov_b32_e32 v17, v143
	v_mov_b32_e32 v19, v143
	v_mov_b32_e32 v21, v143
	v_lshl_add_u64 v[2:3], s[46:47], 0, v[142:143]
	v_lshl_add_u64 v[48:49], v[2:3], 0, v[12:13]
	v_lshl_add_u64 v[26:27], v[2:3], 0, v[14:15]
	v_lshl_add_u64 v[36:37], v[2:3], 0, v[16:17]
	v_lshl_add_u64 v[40:41], v[2:3], 0, v[18:19]
	v_lshl_add_u64 v[2:3], v[2:3], 0, v[20:21]
	s_mov_b32 s10, s48
	s_ashr_i32 s11, s48, 31
	v_lshl_add_u64 v[198:199], s[10:11], 2, v[10:11]
	global_load_dword v200, v[198:199], off
	global_load_dword v201, v[198:199], off offset:64
	global_load_dwordx4 v[22:25], v[48:49], off nt
	s_nop 0
	global_load_dwordx4 v[26:29], v[26:27], off nt
	s_nop 0
	global_load_dwordx4 v[36:39], v[36:37], off nt
	s_nop 0
	global_load_dwordx4 v[40:43], v[40:41], off nt
	s_nop 0
	global_load_dwordx4 v[44:47], v[2:3], off nt
	v_add_co_u32_e32 v2, vcc, s53, v48
	v_add_u32_e32 v35, v30, v31
	s_nop 0
	v_addc_co_u32_e32 v3, vcc, 0, v49, vcc
	v_add_co_u32_e32 v52, vcc, s79, v48
	v_add_u32_e32 v62, 0x420, v35
	s_nop 0
	v_addc_co_u32_e32 v53, vcc, 0, v49, vcc
	v_add_co_u32_e32 v56, vcc, s33, v48
	v_add_u32_e32 v63, 0x428, v35
	s_nop 0
	v_addc_co_u32_e32 v57, vcc, 0, v49, vcc
	global_load_dwordx4 v[48:51], v[2:3], off nt
	s_nop 0
	global_load_dwordx4 v[52:55], v[52:53], off nt
	s_nop 0
	global_load_dwordx4 v[56:59], v[56:57], off nt
	v_add_u32_e32 v65, 0x840, v35
	v_add_u32_e32 v66, 0x848, v35
	v_add_u32_e32 v67, 0xc60, v35
	v_add_u32_e32 v68, 0xc68, v35
	v_add_u32_e32 v69, 0x1080, v35
	v_add_u32_e32 v70, 0x1088, v35
	v_add_u32_e32 v71, 0x14a0, v35
	v_add_u32_e32 v72, 0x14a8, v35
	v_add_u32_e32 v73, 0x18c0, v35
	v_add_u32_e32 v74, 0x18c8, v35
	v_add_u32_e32 v75, 0x1ce0, v35
	v_add_u32_e32 v76, 0x1ce8, v35
	s_ashr_i32 s49, s48, 31
	v_lshl_add_u64 v[4:5], s[48:49], 2, v[10:11]
	s_lshl_b64 s[80:81], s[48:49], 12
	s_add_u32 s46, s51, s80
	s_addc_u32 s47, s52, s81
	s_lshl_b32 s48, s84, 6
	s_ashr_i32 s49, s48, 31
	s_add_u32 s46, s46, s48
	s_addc_u32 s47, s47, s49
	v_lshl_add_u64 v[2:3], s[46:47], 0, v[144:145]
	v_add_u32_e32 v64, 0x400, v149
	v_lshl_add_u64 v[60:61], v[2:3], 0, v[6:7]
	s_add_i32 s45, s45, s8
	s_add_i32 s43, s43, s37
	s_add_i32 s44, s44, s55
	s_cmpk_lt_i32 s45, 0x5600
	s_cbranch_scc0 .Lgu_single
	s_mul_hi_i32 s46, s45, 0x2fa0be83
	s_lshr_b32 s47, s46, 31
	s_ashr_i32 s46, s46, 6
	s_add_i32 s84, s46, s47
	s_mul_i32 s46, s84, 0xffffd500
	s_mul_i32 s47, s84, 0xffffaa00
	s_add_i32 s46, s43, s46
	s_add_i32 s47, s44, s47
	s_and_b32 s48, s46, 0x60
	s_and_b32 s47, s47, 0xffffff00
	s_or_b32 s48, s48, s40
	s_mul_i32 s80, s84, 0x2b0000
	s_or_b32 s48, s48, s47
	s_mul_hi_i32 s49, s84, 0x2b0000
	s_add_u32 s80, s42, s80
	s_addc_u32 s49, s41, s49
	s_ashr_i32 s47, s46, 31
	s_lshl_b64 s[46:47], s[46:47], 2
	s_add_u32 s46, s80, s46
	s_addc_u32 s47, s49, s47
	v_mov_b32_e32 v13, v143
	v_mov_b32_e32 v15, v143
	v_mov_b32_e32 v17, v143
	v_mov_b32_e32 v19, v143
	v_mov_b32_e32 v21, v143
	v_lshl_add_u64 v[238:239], s[46:47], 0, v[142:143]
	v_lshl_add_u64 v[226:227], v[238:239], 0, v[12:13]
	v_lshl_add_u64 v[210:211], v[238:239], 0, v[14:15]
	v_lshl_add_u64 v[214:215], v[238:239], 0, v[16:17]
	v_lshl_add_u64 v[218:219], v[238:239], 0, v[18:19]
	v_lshl_add_u64 v[238:239], v[238:239], 0, v[20:21]
	s_mov_b32 s10, s48
	s_ashr_i32 s11, s48, 31
	v_lshl_add_u64 v[240:241], s[10:11], 2, v[10:11]
	global_load_dword v242, v[240:241], off
	global_load_dword v243, v[240:241], off offset:64
	global_load_dwordx4 v[206:209], v[226:227], off nt
	s_nop 0
	global_load_dwordx4 v[210:213], v[210:211], off nt
	s_nop 0
	global_load_dwordx4 v[214:217], v[214:215], off nt
	s_nop 0
	global_load_dwordx4 v[218:221], v[218:219], off nt
	s_nop 0
	global_load_dwordx4 v[222:225], v[238:239], off nt
	v_add_co_u32_e32 v238, vcc, s53, v226
	v_add_u32_e32 v35, v30, v31
	s_nop 0
	v_addc_co_u32_e32 v239, vcc, 0, v227, vcc
	v_add_co_u32_e32 v230, vcc, s79, v226
	v_add_u32_e32 v62, 0x420, v35
	s_nop 0
	v_addc_co_u32_e32 v231, vcc, 0, v227, vcc
	v_add_co_u32_e32 v234, vcc, s33, v226
	v_add_u32_e32 v63, 0x428, v35
	s_nop 0
	v_addc_co_u32_e32 v235, vcc, 0, v227, vcc
	global_load_dwordx4 v[226:229], v[238:239], off nt
	s_nop 0
	global_load_dwordx4 v[230:233], v[230:231], off nt
	s_nop 0
	global_load_dwordx4 v[234:237], v[234:235], off nt
	s_waitcnt vmcnt(17)
	ds_write2_b32 v35, v22, v23 offset1:1
	ds_write2_b32 v35, v24, v25 offset0:2 offset1:3
	s_waitcnt vmcnt(16)
	ds_write2_b32 v69, v26, v27 offset1:1
	ds_write2_b32 v70, v28, v29 offset1:1
	s_waitcnt vmcnt(15)
	ds_write2_b32 v71, v36, v37 offset1:1
	ds_write2_b32 v72, v38, v39 offset1:1
	s_waitcnt vmcnt(14)
	ds_write2_b32 v73, v40, v41 offset1:1
	ds_write2_b32 v74, v42, v43 offset1:1
	s_waitcnt vmcnt(13)
	ds_write2_b32 v75, v44, v45 offset1:1
	ds_write2_b32 v76, v46, v47 offset1:1
	s_waitcnt vmcnt(12)
	ds_write2_b32 v62, v48, v49 offset1:1
	ds_write2_b32 v63, v50, v51 offset1:1
	s_waitcnt vmcnt(11)
	ds_write2_b32 v65, v52, v53 offset1:1
	ds_write2_b32 v66, v54, v55 offset1:1
	s_waitcnt vmcnt(10)
	ds_write2_b32 v67, v56, v57 offset1:1
	ds_write2_b32 v68, v58, v59 offset1:1
	s_waitcnt lgkmcnt(0)
	v_mov_b32_e32 v13, v200
	ds_read2_b32 v[26:27], v149 offset1:16
	ds_read2_b32 v[28:29], v149 offset0:33 offset1:49
	ds_read2_b32 v[36:37], v149 offset0:66 offset1:82
	ds_read2_b32 v[38:39], v149 offset0:99 offset1:115
	ds_read2_b32 v[40:41], v149 offset0:132 offset1:148
	ds_read2_b32 v[42:43], v149 offset0:165 offset1:181
	ds_read2_b32 v[44:45], v149 offset0:198 offset1:214
	ds_read2_b32 v[46:47], v149 offset0:231 offset1:247
	ds_read2_b32 v[48:49], v64 offset0:8 offset1:24
	ds_read2_b32 v[50:51], v64 offset0:41 offset1:57
	ds_read2_b32 v[52:53], v64 offset0:74 offset1:90
	ds_read2_b32 v[54:55], v64 offset0:107 offset1:123
	ds_read2_b32 v[56:57], v64 offset0:140 offset1:156
	ds_read2_b32 v[58:59], v64 offset0:173 offset1:189
	ds_read2_b32 v[62:63], v64 offset0:206 offset1:222
	ds_read2_b32 v[64:65], v64 offset0:239 offset1:255
	s_waitcnt lgkmcnt(14)
	v_mov_b32_e32 v22, v26
	v_mov_b32_e32 v24, v28
	s_waitcnt lgkmcnt(10)
	v_mov_b32_e32 v25, v42
	v_mov_b32_e32 v68, v38
	s_waitcnt lgkmcnt(8)
	v_mov_b32_e32 v69, v46
	s_waitcnt lgkmcnt(6)
	v_mov_b32_e32 v72, v50
	s_waitcnt lgkmcnt(2)
	v_mov_b32_e32 v73, v58
	v_mov_b32_e32 v74, v52
	s_waitcnt lgkmcnt(1)
	v_mov_b32_e32 v75, v62
	v_mov_b32_e32 v76, v54
	s_waitcnt lgkmcnt(0)
	v_mov_b32_e32 v77, v64
	v_mov_b32_e32 v23, v40
	v_mov_b32_e32 v66, v36
	v_mov_b32_e32 v67, v44
	v_mov_b32_e32 v70, v48
	v_mov_b32_e32 v71, v56
	v_mov_b32_e32 v40, v27
	v_mov_b32_e32 v42, v29
	v_mov_b32_e32 v44, v37
	v_mov_b32_e32 v46, v39
	v_mov_b32_e32 v56, v49
	v_mov_b32_e32 v58, v51
	v_mov_b32_e32 v62, v53
	v_mov_b32_e32 v64, v55
	s_nop 0
	v_div_scale_f32 v15, s[46:47], v13, v13, s90
	v_rcp_f32_e32 v19, v15
	v_div_scale_f32 v17, vcc, s90, v13, s90
	v_fma_f32 v21, -v15, v19, 1.0
	v_fmac_f32_e32 v19, v21, v19
	v_mul_f32_e32 v21, v17, v19
	v_fma_f32 v26, -v15, v21, v17
	v_fmac_f32_e32 v21, v26, v19
	v_fma_f32 v15, -v15, v21, v17
	v_div_fmas_f32 v15, v15, v19, v21
	v_div_fixup_f32 v15, v15, v13, s90
	v_cmp_lt_f32_e32 vcc, 0, v13
	s_nop 1
	v_cndmask_b32_e32 v26, 0, v15, vcc
	v_pk_fma_f32 v[24:25], v[24:25], v[26:27], s[78:79] op_sel_hi:[1,0,0]
	v_pk_fma_f32 v[68:69], v[68:69], v[26:27], s[78:79] op_sel_hi:[1,0,0]
	v_pk_fma_f32 v[72:73], v[72:73], v[26:27], s[78:79] op_sel_hi:[1,0,0]
	v_pk_fma_f32 v[74:75], v[74:75], v[26:27], s[78:79] op_sel_hi:[1,0,0]
	v_pk_fma_f32 v[76:77], v[76:77], v[26:27], s[78:79] op_sel_hi:[1,0,0]
	v_pk_fma_f32 v[22:23], v[22:23], v[26:27], s[78:79] op_sel_hi:[1,0,0]
	v_pk_fma_f32 v[66:67], v[66:67], v[26:27], s[78:79] op_sel_hi:[1,0,0]
	v_pk_fma_f32 v[70:71], v[70:71], v[26:27], s[78:79] op_sel_hi:[1,0,0]
	v_lshlrev_b32_e32 v13, 8, v25
	v_lshlrev_b32_e32 v15, 8, v24
	v_lshlrev_b32_e32 v21, 24, v69
	v_lshlrev_b32_e32 v24, 24, v68
	v_lshlrev_b32_e32 v25, 8, v73
	v_lshlrev_b32_e32 v26, 8, v72
	v_lshlrev_b32_e32 v28, 16, v75
	v_lshlrev_b32_e32 v35, 16, v74
	v_lshlrev_b32_e32 v36, 24, v77
	v_lshlrev_b32_e32 v38, 24, v76
	v_lshlrev_b32_e32 v17, 16, v67
	v_lshlrev_b32_e32 v19, 16, v66
	v_and_b32_e32 v13, 0xff00, v13
	v_and_b32_e32 v15, 0xff00, v15
	v_or_b32_sdwa v21, v21, v23 dst_sel:DWORD dst_unused:UNUSED_PAD src0_sel:DWORD src1_sel:BYTE_0
	v_or_b32_sdwa v22, v24, v22 dst_sel:DWORD dst_unused:UNUSED_PAD src0_sel:DWORD src1_sel:BYTE_0
	v_and_b32_e32 v23, 0xff00, v25
	v_and_b32_e32 v24, 0xff00, v26
	v_and_b32_e32 v25, 0xff0000, v28
	v_and_b32_e32 v26, 0xff0000, v35
	v_or_b32_sdwa v28, v36, v71 dst_sel:DWORD dst_unused:UNUSED_PAD src0_sel:DWORD src1_sel:BYTE_0
	v_or_b32_sdwa v35, v38, v70 dst_sel:DWORD dst_unused:UNUSED_PAD src0_sel:DWORD src1_sel:BYTE_0
	v_and_b32_e32 v17, 0xff0000, v17
	v_and_b32_e32 v19, 0xff0000, v19
	v_or_b32_e32 v13, v21, v13
	v_or_b32_e32 v15, v22, v15
	v_or_b32_e32 v21, v28, v23
	v_or_b32_e32 v24, v35, v24
	v_or_b32_e32 v23, v13, v17
	v_or_b32_e32 v22, v15, v19
	v_or_b32_e32 v25, v21, v25
	v_or_b32_e32 v24, v24, v26
	global_store_dwordx4 v[60:61], v[22:25], off
	v_mov_b32_e32 v4, v201
	s_nop 0
	v_lshl_add_u64 v[22:23], v[2:3], 0, v[146:147]
	s_nop 0
	v_div_scale_f32 v2, s[46:47], v4, v4, s90
	v_rcp_f32_e32 v5, v2
	v_div_scale_f32 v3, vcc, s90, v4, s90
	v_fma_f32 v13, -v2, v5, 1.0
	v_fmac_f32_e32 v5, v13, v5
	v_mul_f32_e32 v13, v3, v5
	v_fma_f32 v15, -v2, v13, v3
	v_fmac_f32_e32 v13, v15, v5
	v_fma_f32 v2, -v2, v13, v3
	v_div_fmas_f32 v2, v2, v5, v13
	v_div_fixup_f32 v2, v2, v4, s90
	v_cmp_lt_f32_e32 vcc, 0, v4
	s_nop 1
	v_cndmask_b32_e32 v2, 0, v2, vcc
	v_pk_fma_f32 v[4:5], v[40:41], v[2:3], s[78:79] op_sel_hi:[1,0,0]
	v_pk_fma_f32 v[24:25], v[42:43], v[2:3], s[78:79] op_sel_hi:[1,0,0]
	v_pk_fma_f32 v[26:27], v[44:45], v[2:3], s[78:79] op_sel_hi:[1,0,0]
	v_pk_fma_f32 v[28:29], v[46:47], v[2:3], s[78:79] op_sel_hi:[1,0,0]
	v_pk_fma_f32 v[36:37], v[56:57], v[2:3], s[78:79] op_sel_hi:[1,0,0]
	v_pk_fma_f32 v[38:39], v[58:59], v[2:3], s[78:79] op_sel_hi:[1,0,0]
	v_pk_fma_f32 v[40:41], v[62:63], v[2:3], s[78:79] op_sel_hi:[1,0,0]
	v_pk_fma_f32 v[2:3], v[64:65], v[2:3], s[78:79] op_sel_hi:[1,0,0]
	v_lshlrev_b32_e32 v13, 8, v25
	v_lshlrev_b32_e32 v15, 8, v24
	v_lshlrev_b32_e32 v19, 16, v26
	v_lshlrev_b32_e32 v21, 24, v29
	v_lshlrev_b32_e32 v24, 24, v28
	v_lshlrev_b32_e32 v25, 8, v39
	v_lshlrev_b32_e32 v26, 8, v38
	v_lshlrev_b32_e32 v3, 24, v3
	v_lshlrev_b32_e32 v2, 24, v2
	v_lshlrev_b32_e32 v17, 16, v27
	v_lshlrev_b32_e32 v27, 16, v41
	v_lshlrev_b32_e32 v28, 16, v40
	v_and_b32_e32 v13, 0xff00, v13
	v_and_b32_e32 v15, 0xff00, v15
	v_or_b32_sdwa v5, v21, v5 dst_sel:DWORD dst_unused:UNUSED_PAD src0_sel:DWORD src1_sel:BYTE_0
	v_or_b32_sdwa v4, v24, v4 dst_sel:DWORD dst_unused:UNUSED_PAD src0_sel:DWORD src1_sel:BYTE_0
	v_and_b32_e32 v21, 0xff00, v25
	v_and_b32_e32 v24, 0xff00, v26
	v_or_b32_sdwa v3, v3, v37 dst_sel:DWORD dst_unused:UNUSED_PAD src0_sel:DWORD src1_sel:BYTE_0
	v_or_b32_sdwa v2, v2, v36 dst_sel:DWORD dst_unused:UNUSED_PAD src0_sel:DWORD src1_sel:BYTE_0
	v_and_b32_e32 v17, 0xff0000, v17
	v_and_b32_e32 v19, 0xff0000, v19
	v_and_b32_e32 v25, 0xff0000, v27
	v_and_b32_e32 v26, 0xff0000, v28
	v_or_b32_e32 v5, v5, v13
	v_or_b32_e32 v4, v4, v15
	v_or_b32_e32 v13, v3, v21
	v_or_b32_e32 v15, v2, v24
	v_or_b32_e32 v3, v5, v17
	v_or_b32_e32 v2, v4, v19
	v_or_b32_e32 v5, v13, v25
	v_or_b32_e32 v4, v15, v26
	global_store_dwordx4 v[22:23], v[2:5], off
	s_waitcnt lgkmcnt(0)
	s_mul_hi_i32 s46, s45, 0x2fa0be83
	s_lshr_b32 s47, s46, 31
	s_ashr_i32 s46, s46, 6
	s_add_i32 s84, s46, s47
	s_mul_i32 s46, s84, 0xffffd500
	s_mul_i32 s47, s84, 0xffffaa00
	s_add_i32 s46, s43, s46
	s_add_i32 s47, s44, s47
	s_and_b32 s48, s46, 0x60
	s_and_b32 s47, s47, 0xffffff00
	s_or_b32 s48, s48, s40
	s_mul_i32 s80, s84, 0x2b0000
	s_or_b32 s48, s48, s47
	s_mul_hi_i32 s49, s84, 0x2b0000
	s_add_u32 s80, s42, s80
	s_addc_u32 s49, s41, s49
	s_ashr_i32 s47, s46, 31
	s_lshl_b64 s[46:47], s[46:47], 2
	s_add_u32 s46, s80, s46
	s_addc_u32 s47, s49, s47
	v_mov_b32_e32 v13, v143
	v_mov_b32_e32 v15, v143
	v_mov_b32_e32 v17, v143
	v_mov_b32_e32 v19, v143
	v_mov_b32_e32 v21, v143
	v_lshl_add_u64 v[2:3], s[46:47], 0, v[142:143]
	v_lshl_add_u64 v[48:49], v[2:3], 0, v[12:13]
	v_lshl_add_u64 v[26:27], v[2:3], 0, v[14:15]
	v_lshl_add_u64 v[36:37], v[2:3], 0, v[16:17]
	v_lshl_add_u64 v[40:41], v[2:3], 0, v[18:19]
	v_lshl_add_u64 v[2:3], v[2:3], 0, v[20:21]
	s_mov_b32 s10, s48
	s_ashr_i32 s11, s48, 31
	v_lshl_add_u64 v[198:199], s[10:11], 2, v[10:11]
	s_nop 0
	s_nop 0
	s_nop 0
	s_nop 0
	v_add_co_u32_e32 v2, vcc, s53, v48
	v_add_u32_e32 v35, v30, v31
	s_nop 0
	v_addc_co_u32_e32 v3, vcc, 0, v49, vcc
	v_add_co_u32_e32 v52, vcc, s79, v48
	v_add_u32_e32 v62, 0x420, v35
	s_nop 0
	v_addc_co_u32_e32 v53, vcc, 0, v49, vcc
	v_add_co_u32_e32 v56, vcc, s33, v48
	v_add_u32_e32 v63, 0x428, v35
	s_nop 0
	v_addc_co_u32_e32 v57, vcc, 0, v49, vcc
	s_nop 0
	s_nop 0
	v_add_u32_e32 v65, 0x840, v35
	v_add_u32_e32 v66, 0x848, v35
	v_add_u32_e32 v67, 0xc60, v35
	v_add_u32_e32 v68, 0xc68, v35
	v_add_u32_e32 v69, 0x1080, v35
	v_add_u32_e32 v70, 0x1088, v35
	v_add_u32_e32 v71, 0x14a0, v35
	v_add_u32_e32 v72, 0x14a8, v35
	v_add_u32_e32 v73, 0x18c0, v35
	v_add_u32_e32 v74, 0x18c8, v35
	v_add_u32_e32 v75, 0x1ce0, v35
	v_add_u32_e32 v76, 0x1ce8, v35
	s_ashr_i32 s49, s48, 31
	v_lshl_add_u64 v[4:5], s[48:49], 2, v[10:11]
	s_lshl_b64 s[80:81], s[48:49], 12
	s_add_u32 s46, s51, s80
	s_addc_u32 s47, s52, s81
	s_lshl_b32 s48, s84, 6
	s_ashr_i32 s49, s48, 31
	s_add_u32 s46, s46, s48
	s_addc_u32 s47, s47, s49
	v_lshl_add_u64 v[2:3], s[46:47], 0, v[144:145]
	v_add_u32_e32 v64, 0x400, v149
	v_lshl_add_u64 v[60:61], v[2:3], 0, v[6:7]
	s_add_i32 s45, s45, s8
	s_add_i32 s43, s43, s37
	s_add_i32 s44, s44, s55
	s_cmpk_lt_i32 s45, 0x5600
	s_waitcnt vmcnt(9)
	ds_write2_b32 v35, v206, v207 offset1:1
	ds_write2_b32 v35, v208, v209 offset0:2 offset1:3
	s_waitcnt vmcnt(8)
	ds_write2_b32 v69, v210, v211 offset1:1
	ds_write2_b32 v70, v212, v213 offset1:1
	s_waitcnt vmcnt(7)
	ds_write2_b32 v71, v214, v215 offset1:1
	ds_write2_b32 v72, v216, v217 offset1:1
	s_waitcnt vmcnt(6)
	ds_write2_b32 v73, v218, v219 offset1:1
	ds_write2_b32 v74, v220, v221 offset1:1
	s_waitcnt vmcnt(5)
	ds_write2_b32 v75, v222, v223 offset1:1
	ds_write2_b32 v76, v224, v225 offset1:1
	s_waitcnt vmcnt(4)
	ds_write2_b32 v62, v226, v227 offset1:1
	ds_write2_b32 v63, v228, v229 offset1:1
	s_waitcnt vmcnt(3)
	ds_write2_b32 v65, v230, v231 offset1:1
	ds_write2_b32 v66, v232, v233 offset1:1
	s_waitcnt vmcnt(2)
	ds_write2_b32 v67, v234, v235 offset1:1
	ds_write2_b32 v68, v236, v237 offset1:1
	s_waitcnt lgkmcnt(0)
	v_mov_b32_e32 v13, v242
	ds_read2_b32 v[26:27], v149 offset1:16
	ds_read2_b32 v[28:29], v149 offset0:33 offset1:49
	ds_read2_b32 v[36:37], v149 offset0:66 offset1:82
	ds_read2_b32 v[38:39], v149 offset0:99 offset1:115
	ds_read2_b32 v[40:41], v149 offset0:132 offset1:148
	ds_read2_b32 v[42:43], v149 offset0:165 offset1:181
	ds_read2_b32 v[44:45], v149 offset0:198 offset1:214
	ds_read2_b32 v[46:47], v149 offset0:231 offset1:247
	ds_read2_b32 v[48:49], v64 offset0:8 offset1:24
	ds_read2_b32 v[50:51], v64 offset0:41 offset1:57
	ds_read2_b32 v[52:53], v64 offset0:74 offset1:90
	ds_read2_b32 v[54:55], v64 offset0:107 offset1:123
	ds_read2_b32 v[56:57], v64 offset0:140 offset1:156
	ds_read2_b32 v[58:59], v64 offset0:173 offset1:189
	ds_read2_b32 v[62:63], v64 offset0:206 offset1:222
	ds_read2_b32 v[64:65], v64 offset0:239 offset1:255
	s_waitcnt lgkmcnt(14)
	v_mov_b32_e32 v22, v26
	v_mov_b32_e32 v24, v28
	s_waitcnt lgkmcnt(10)
	v_mov_b32_e32 v25, v42
	v_mov_b32_e32 v68, v38
	s_waitcnt lgkmcnt(8)
	v_mov_b32_e32 v69, v46
	s_waitcnt lgkmcnt(6)
	v_mov_b32_e32 v72, v50
	s_waitcnt lgkmcnt(2)
	v_mov_b32_e32 v73, v58
	v_mov_b32_e32 v74, v52
	s_waitcnt lgkmcnt(1)
	v_mov_b32_e32 v75, v62
	v_mov_b32_e32 v76, v54
	s_waitcnt lgkmcnt(0)
	v_mov_b32_e32 v77, v64
	v_mov_b32_e32 v23, v40
	v_mov_b32_e32 v66, v36
	v_mov_b32_e32 v67, v44
	v_mov_b32_e32 v70, v48
	v_mov_b32_e32 v71, v56
	v_mov_b32_e32 v40, v27
	v_mov_b32_e32 v42, v29
	v_mov_b32_e32 v44, v37
	v_mov_b32_e32 v46, v39
	v_mov_b32_e32 v56, v49
	v_mov_b32_e32 v58, v51
	v_mov_b32_e32 v62, v53
	v_mov_b32_e32 v64, v55
	s_nop 0
	v_div_scale_f32 v15, s[46:47], v13, v13, s90
	v_rcp_f32_e32 v19, v15
	v_div_scale_f32 v17, vcc, s90, v13, s90
	v_fma_f32 v21, -v15, v19, 1.0
	v_fmac_f32_e32 v19, v21, v19
	v_mul_f32_e32 v21, v17, v19
	v_fma_f32 v26, -v15, v21, v17
	v_fmac_f32_e32 v21, v26, v19
	v_fma_f32 v15, -v15, v21, v17
	v_div_fmas_f32 v15, v15, v19, v21
	v_div_fixup_f32 v15, v15, v13, s90
	v_cmp_lt_f32_e32 vcc, 0, v13
	s_nop 1
	v_cndmask_b32_e32 v26, 0, v15, vcc
	v_pk_fma_f32 v[24:25], v[24:25], v[26:27], s[78:79] op_sel_hi:[1,0,0]
	v_pk_fma_f32 v[68:69], v[68:69], v[26:27], s[78:79] op_sel_hi:[1,0,0]
	v_pk_fma_f32 v[72:73], v[72:73], v[26:27], s[78:79] op_sel_hi:[1,0,0]
	v_pk_fma_f32 v[74:75], v[74:75], v[26:27], s[78:79] op_sel_hi:[1,0,0]
	v_pk_fma_f32 v[76:77], v[76:77], v[26:27], s[78:79] op_sel_hi:[1,0,0]
	v_pk_fma_f32 v[22:23], v[22:23], v[26:27], s[78:79] op_sel_hi:[1,0,0]
	v_pk_fma_f32 v[66:67], v[66:67], v[26:27], s[78:79] op_sel_hi:[1,0,0]
	v_pk_fma_f32 v[70:71], v[70:71], v[26:27], s[78:79] op_sel_hi:[1,0,0]
	v_lshlrev_b32_e32 v13, 8, v25
	v_lshlrev_b32_e32 v15, 8, v24
	v_lshlrev_b32_e32 v21, 24, v69
	v_lshlrev_b32_e32 v24, 24, v68
	v_lshlrev_b32_e32 v25, 8, v73
	v_lshlrev_b32_e32 v26, 8, v72
	v_lshlrev_b32_e32 v28, 16, v75
	v_lshlrev_b32_e32 v35, 16, v74
	v_lshlrev_b32_e32 v36, 24, v77
	v_lshlrev_b32_e32 v38, 24, v76
	v_lshlrev_b32_e32 v17, 16, v67
	v_lshlrev_b32_e32 v19, 16, v66
	v_and_b32_e32 v13, 0xff00, v13
	v_and_b32_e32 v15, 0xff00, v15
	v_or_b32_sdwa v21, v21, v23 dst_sel:DWORD dst_unused:UNUSED_PAD src0_sel:DWORD src1_sel:BYTE_0
	v_or_b32_sdwa v22, v24, v22 dst_sel:DWORD dst_unused:UNUSED_PAD src0_sel:DWORD src1_sel:BYTE_0
	v_and_b32_e32 v23, 0xff00, v25
	v_and_b32_e32 v24, 0xff00, v26
	v_and_b32_e32 v25, 0xff0000, v28
	v_and_b32_e32 v26, 0xff0000, v35
	v_or_b32_sdwa v28, v36, v71 dst_sel:DWORD dst_unused:UNUSED_PAD src0_sel:DWORD src1_sel:BYTE_0
	v_or_b32_sdwa v35, v38, v70 dst_sel:DWORD dst_unused:UNUSED_PAD src0_sel:DWORD src1_sel:BYTE_0
	v_and_b32_e32 v17, 0xff0000, v17
	v_and_b32_e32 v19, 0xff0000, v19
	v_or_b32_e32 v13, v21, v13
	v_or_b32_e32 v15, v22, v15
	v_or_b32_e32 v21, v28, v23
	v_or_b32_e32 v24, v35, v24
	v_or_b32_e32 v23, v13, v17
	v_or_b32_e32 v22, v15, v19
	v_or_b32_e32 v25, v21, v25
	v_or_b32_e32 v24, v24, v26
	global_store_dwordx4 v[60:61], v[22:25], off
	v_mov_b32_e32 v4, v243
	s_nop 0
	v_lshl_add_u64 v[22:23], v[2:3], 0, v[146:147]
	s_nop 0
	v_div_scale_f32 v2, s[46:47], v4, v4, s90
	v_rcp_f32_e32 v5, v2
	v_div_scale_f32 v3, vcc, s90, v4, s90
	v_fma_f32 v13, -v2, v5, 1.0
	v_fmac_f32_e32 v5, v13, v5
	v_mul_f32_e32 v13, v3, v5
	v_fma_f32 v15, -v2, v13, v3
	v_fmac_f32_e32 v13, v15, v5
	v_fma_f32 v2, -v2, v13, v3
	v_div_fmas_f32 v2, v2, v5, v13
	v_div_fixup_f32 v2, v2, v4, s90
	v_cmp_lt_f32_e32 vcc, 0, v4
	s_nop 1
	v_cndmask_b32_e32 v2, 0, v2, vcc
	v_pk_fma_f32 v[4:5], v[40:41], v[2:3], s[78:79] op_sel_hi:[1,0,0]
	v_pk_fma_f32 v[24:25], v[42:43], v[2:3], s[78:79] op_sel_hi:[1,0,0]
	v_pk_fma_f32 v[26:27], v[44:45], v[2:3], s[78:79] op_sel_hi:[1,0,0]
	v_pk_fma_f32 v[28:29], v[46:47], v[2:3], s[78:79] op_sel_hi:[1,0,0]
	v_pk_fma_f32 v[36:37], v[56:57], v[2:3], s[78:79] op_sel_hi:[1,0,0]
	v_pk_fma_f32 v[38:39], v[58:59], v[2:3], s[78:79] op_sel_hi:[1,0,0]
	v_pk_fma_f32 v[40:41], v[62:63], v[2:3], s[78:79] op_sel_hi:[1,0,0]
	v_pk_fma_f32 v[2:3], v[64:65], v[2:3], s[78:79] op_sel_hi:[1,0,0]
	v_lshlrev_b32_e32 v13, 8, v25
	v_lshlrev_b32_e32 v15, 8, v24
	v_lshlrev_b32_e32 v19, 16, v26
	v_lshlrev_b32_e32 v21, 24, v29
	v_lshlrev_b32_e32 v24, 24, v28
	v_lshlrev_b32_e32 v25, 8, v39
	v_lshlrev_b32_e32 v26, 8, v38
	v_lshlrev_b32_e32 v3, 24, v3
	v_lshlrev_b32_e32 v2, 24, v2
	v_lshlrev_b32_e32 v17, 16, v27
	v_lshlrev_b32_e32 v27, 16, v41
	v_lshlrev_b32_e32 v28, 16, v40
	v_and_b32_e32 v13, 0xff00, v13
	v_and_b32_e32 v15, 0xff00, v15
	v_or_b32_sdwa v5, v21, v5 dst_sel:DWORD dst_unused:UNUSED_PAD src0_sel:DWORD src1_sel:BYTE_0
	v_or_b32_sdwa v4, v24, v4 dst_sel:DWORD dst_unused:UNUSED_PAD src0_sel:DWORD src1_sel:BYTE_0
	v_and_b32_e32 v21, 0xff00, v25
	v_and_b32_e32 v24, 0xff00, v26
	v_or_b32_sdwa v3, v3, v37 dst_sel:DWORD dst_unused:UNUSED_PAD src0_sel:DWORD src1_sel:BYTE_0
	v_or_b32_sdwa v2, v2, v36 dst_sel:DWORD dst_unused:UNUSED_PAD src0_sel:DWORD src1_sel:BYTE_0
	v_and_b32_e32 v17, 0xff0000, v17
	v_and_b32_e32 v19, 0xff0000, v19
	v_and_b32_e32 v25, 0xff0000, v27
	v_and_b32_e32 v26, 0xff0000, v28
	v_or_b32_e32 v5, v5, v13
	v_or_b32_e32 v4, v4, v15
	v_or_b32_e32 v13, v3, v21
	v_or_b32_e32 v15, v2, v24
	v_or_b32_e32 v3, v5, v17
	v_or_b32_e32 v2, v4, v19
	v_or_b32_e32 v5, v13, v25
	v_or_b32_e32 v4, v15, v26
	global_store_dwordx4 v[22:23], v[2:5], off
	s_waitcnt lgkmcnt(0)
	s_cbranch_scc1 .LBB0_65
	s_branch .LBB0_7
.Lgu_single:
	s_waitcnt vmcnt(7)
	ds_write2_b32 v35, v22, v23 offset1:1
	ds_write2_b32 v35, v24, v25 offset0:2 offset1:3
	s_waitcnt vmcnt(6)
	ds_write2_b32 v69, v26, v27 offset1:1
	ds_write2_b32 v70, v28, v29 offset1:1
	s_waitcnt vmcnt(5)
	ds_write2_b32 v71, v36, v37 offset1:1
	ds_write2_b32 v72, v38, v39 offset1:1
	s_waitcnt vmcnt(4)
	ds_write2_b32 v73, v40, v41 offset1:1
	ds_write2_b32 v74, v42, v43 offset1:1
	s_waitcnt vmcnt(3)
	ds_write2_b32 v75, v44, v45 offset1:1
	ds_write2_b32 v76, v46, v47 offset1:1
	s_waitcnt vmcnt(2)
	ds_write2_b32 v62, v48, v49 offset1:1
	ds_write2_b32 v63, v50, v51 offset1:1
	s_waitcnt vmcnt(1)
	ds_write2_b32 v65, v52, v53 offset1:1
	ds_write2_b32 v66, v54, v55 offset1:1
	s_waitcnt vmcnt(0)
	ds_write2_b32 v67, v56, v57 offset1:1
	ds_write2_b32 v68, v58, v59 offset1:1
	s_waitcnt lgkmcnt(0)
	v_mov_b32_e32 v13, v200
	ds_read2_b32 v[26:27], v149 offset1:16
	ds_read2_b32 v[28:29], v149 offset0:33 offset1:49
	ds_read2_b32 v[36:37], v149 offset0:66 offset1:82
	ds_read2_b32 v[38:39], v149 offset0:99 offset1:115
	ds_read2_b32 v[40:41], v149 offset0:132 offset1:148
	ds_read2_b32 v[42:43], v149 offset0:165 offset1:181
	ds_read2_b32 v[44:45], v149 offset0:198 offset1:214
	ds_read2_b32 v[46:47], v149 offset0:231 offset1:247
	ds_read2_b32 v[48:49], v64 offset0:8 offset1:24
	ds_read2_b32 v[50:51], v64 offset0:41 offset1:57
	ds_read2_b32 v[52:53], v64 offset0:74 offset1:90
	ds_read2_b32 v[54:55], v64 offset0:107 offset1:123
	ds_read2_b32 v[56:57], v64 offset0:140 offset1:156
	ds_read2_b32 v[58:59], v64 offset0:173 offset1:189
	ds_read2_b32 v[62:63], v64 offset0:206 offset1:222
	ds_read2_b32 v[64:65], v64 offset0:239 offset1:255
	s_waitcnt lgkmcnt(14)
	v_mov_b32_e32 v22, v26
	v_mov_b32_e32 v24, v28
	s_waitcnt lgkmcnt(10)
	v_mov_b32_e32 v25, v42
	v_mov_b32_e32 v68, v38
	s_waitcnt lgkmcnt(8)
	v_mov_b32_e32 v69, v46
	s_waitcnt lgkmcnt(6)
	v_mov_b32_e32 v72, v50
	s_waitcnt lgkmcnt(2)
	v_mov_b32_e32 v73, v58
	v_mov_b32_e32 v74, v52
	s_waitcnt lgkmcnt(1)
	v_mov_b32_e32 v75, v62
	v_mov_b32_e32 v76, v54
	s_waitcnt lgkmcnt(0)
	v_mov_b32_e32 v77, v64
	v_mov_b32_e32 v23, v40
	v_mov_b32_e32 v66, v36
	v_mov_b32_e32 v67, v44
	v_mov_b32_e32 v70, v48
	v_mov_b32_e32 v71, v56
	v_mov_b32_e32 v40, v27
	v_mov_b32_e32 v42, v29
	v_mov_b32_e32 v44, v37
	v_mov_b32_e32 v46, v39
	v_mov_b32_e32 v56, v49
	v_mov_b32_e32 v58, v51
	v_mov_b32_e32 v62, v53
	v_mov_b32_e32 v64, v55
	s_nop 0
	v_div_scale_f32 v15, s[46:47], v13, v13, s90
	v_rcp_f32_e32 v19, v15
	v_div_scale_f32 v17, vcc, s90, v13, s90
	v_fma_f32 v21, -v15, v19, 1.0
	v_fmac_f32_e32 v19, v21, v19
	v_mul_f32_e32 v21, v17, v19
	v_fma_f32 v26, -v15, v21, v17
	v_fmac_f32_e32 v21, v26, v19
	v_fma_f32 v15, -v15, v21, v17
	v_div_fmas_f32 v15, v15, v19, v21
	v_div_fixup_f32 v15, v15, v13, s90
	v_cmp_lt_f32_e32 vcc, 0, v13
	s_nop 1
	v_cndmask_b32_e32 v26, 0, v15, vcc
	v_pk_fma_f32 v[24:25], v[24:25], v[26:27], s[78:79] op_sel_hi:[1,0,0]
	v_pk_fma_f32 v[68:69], v[68:69], v[26:27], s[78:79] op_sel_hi:[1,0,0]
	v_pk_fma_f32 v[72:73], v[72:73], v[26:27], s[78:79] op_sel_hi:[1,0,0]
	v_pk_fma_f32 v[74:75], v[74:75], v[26:27], s[78:79] op_sel_hi:[1,0,0]
	v_pk_fma_f32 v[76:77], v[76:77], v[26:27], s[78:79] op_sel_hi:[1,0,0]
	v_pk_fma_f32 v[22:23], v[22:23], v[26:27], s[78:79] op_sel_hi:[1,0,0]
	v_pk_fma_f32 v[66:67], v[66:67], v[26:27], s[78:79] op_sel_hi:[1,0,0]
	v_pk_fma_f32 v[70:71], v[70:71], v[26:27], s[78:79] op_sel_hi:[1,0,0]
	v_lshlrev_b32_e32 v13, 8, v25
	v_lshlrev_b32_e32 v15, 8, v24
	v_lshlrev_b32_e32 v21, 24, v69
	v_lshlrev_b32_e32 v24, 24, v68
	v_lshlrev_b32_e32 v25, 8, v73
	v_lshlrev_b32_e32 v26, 8, v72
	v_lshlrev_b32_e32 v28, 16, v75
	v_lshlrev_b32_e32 v35, 16, v74
	v_lshlrev_b32_e32 v36, 24, v77
	v_lshlrev_b32_e32 v38, 24, v76
	v_lshlrev_b32_e32 v17, 16, v67
	v_lshlrev_b32_e32 v19, 16, v66
	v_and_b32_e32 v13, 0xff00, v13
	v_and_b32_e32 v15, 0xff00, v15
	v_or_b32_sdwa v21, v21, v23 dst_sel:DWORD dst_unused:UNUSED_PAD src0_sel:DWORD src1_sel:BYTE_0
	v_or_b32_sdwa v22, v24, v22 dst_sel:DWORD dst_unused:UNUSED_PAD src0_sel:DWORD src1_sel:BYTE_0
	v_and_b32_e32 v23, 0xff00, v25
	v_and_b32_e32 v24, 0xff00, v26
	v_and_b32_e32 v25, 0xff0000, v28
	v_and_b32_e32 v26, 0xff0000, v35
	v_or_b32_sdwa v28, v36, v71 dst_sel:DWORD dst_unused:UNUSED_PAD src0_sel:DWORD src1_sel:BYTE_0
	v_or_b32_sdwa v35, v38, v70 dst_sel:DWORD dst_unused:UNUSED_PAD src0_sel:DWORD src1_sel:BYTE_0
	v_and_b32_e32 v17, 0xff0000, v17
	v_and_b32_e32 v19, 0xff0000, v19
	v_or_b32_e32 v13, v21, v13
	v_or_b32_e32 v15, v22, v15
	v_or_b32_e32 v21, v28, v23
	v_or_b32_e32 v24, v35, v24
	v_or_b32_e32 v23, v13, v17
	v_or_b32_e32 v22, v15, v19
	v_or_b32_e32 v25, v21, v25
	v_or_b32_e32 v24, v24, v26
	global_store_dwordx4 v[60:61], v[22:25], off
	v_mov_b32_e32 v4, v201
	s_nop 0
	v_lshl_add_u64 v[22:23], v[2:3], 0, v[146:147]
	s_nop 0
	v_div_scale_f32 v2, s[46:47], v4, v4, s90
	v_rcp_f32_e32 v5, v2
	v_div_scale_f32 v3, vcc, s90, v4, s90
	v_fma_f32 v13, -v2, v5, 1.0
	v_fmac_f32_e32 v5, v13, v5
	v_mul_f32_e32 v13, v3, v5
	v_fma_f32 v15, -v2, v13, v3
	v_fmac_f32_e32 v13, v15, v5
	v_fma_f32 v2, -v2, v13, v3
	v_div_fmas_f32 v2, v2, v5, v13
	v_div_fixup_f32 v2, v2, v4, s90
	v_cmp_lt_f32_e32 vcc, 0, v4
	s_nop 1
	v_cndmask_b32_e32 v2, 0, v2, vcc
	v_pk_fma_f32 v[4:5], v[40:41], v[2:3], s[78:79] op_sel_hi:[1,0,0]
	v_pk_fma_f32 v[24:25], v[42:43], v[2:3], s[78:79] op_sel_hi:[1,0,0]
	v_pk_fma_f32 v[26:27], v[44:45], v[2:3], s[78:79] op_sel_hi:[1,0,0]
	v_pk_fma_f32 v[28:29], v[46:47], v[2:3], s[78:79] op_sel_hi:[1,0,0]
	v_pk_fma_f32 v[36:37], v[56:57], v[2:3], s[78:79] op_sel_hi:[1,0,0]
	v_pk_fma_f32 v[38:39], v[58:59], v[2:3], s[78:79] op_sel_hi:[1,0,0]
	v_pk_fma_f32 v[40:41], v[62:63], v[2:3], s[78:79] op_sel_hi:[1,0,0]
	v_pk_fma_f32 v[2:3], v[64:65], v[2:3], s[78:79] op_sel_hi:[1,0,0]
	v_lshlrev_b32_e32 v13, 8, v25
	v_lshlrev_b32_e32 v15, 8, v24
	v_lshlrev_b32_e32 v19, 16, v26
	v_lshlrev_b32_e32 v21, 24, v29
	v_lshlrev_b32_e32 v24, 24, v28
	v_lshlrev_b32_e32 v25, 8, v39
	v_lshlrev_b32_e32 v26, 8, v38
	v_lshlrev_b32_e32 v3, 24, v3
	v_lshlrev_b32_e32 v2, 24, v2
	v_lshlrev_b32_e32 v17, 16, v27
	v_lshlrev_b32_e32 v27, 16, v41
	v_lshlrev_b32_e32 v28, 16, v40
	v_and_b32_e32 v13, 0xff00, v13
	v_and_b32_e32 v15, 0xff00, v15
	v_or_b32_sdwa v5, v21, v5 dst_sel:DWORD dst_unused:UNUSED_PAD src0_sel:DWORD src1_sel:BYTE_0
	v_or_b32_sdwa v4, v24, v4 dst_sel:DWORD dst_unused:UNUSED_PAD src0_sel:DWORD src1_sel:BYTE_0
	v_and_b32_e32 v21, 0xff00, v25
	v_and_b32_e32 v24, 0xff00, v26
	v_or_b32_sdwa v3, v3, v37 dst_sel:DWORD dst_unused:UNUSED_PAD src0_sel:DWORD src1_sel:BYTE_0
	v_or_b32_sdwa v2, v2, v36 dst_sel:DWORD dst_unused:UNUSED_PAD src0_sel:DWORD src1_sel:BYTE_0
	v_and_b32_e32 v17, 0xff0000, v17
	v_and_b32_e32 v19, 0xff0000, v19
	v_and_b32_e32 v25, 0xff0000, v27
	v_and_b32_e32 v26, 0xff0000, v28
	v_or_b32_e32 v5, v5, v13
	v_or_b32_e32 v4, v4, v15
	v_or_b32_e32 v13, v3, v21
	v_or_b32_e32 v15, v2, v24
	v_or_b32_e32 v3, v5, v17
	v_or_b32_e32 v2, v4, v19
	v_or_b32_e32 v5, v13, v25
	v_or_b32_e32 v4, v15, v26
	global_store_dwordx4 v[22:23], v[2:5], off
	s_waitcnt lgkmcnt(0)
	s_branch .LBB0_7
